# P2 K-loop v2: 2-set fragment ping-pong, barrier rotated between MFMA group 2 and 3, next-step LDS reads + LDS-DMA under group 3
# speedup vs baseline: 1.0121x; 1.0089x over previous
; DI int tid_() { int t = threadIdx.x; asm volatile("" : "+v"(t)); return t; }
; DI void wait_vm0() { asm volatile("s_waitcnt vmcnt(0)" ::: "memory"); }
; DI void bar_() { __builtin_amdgcn_s_barrier(); }
; template <int TM, int TN, int WM, int WN, bool SUMSQ, int NST, class AF, class BF, class AFN, class BFN>
; DI void gemm8x(f32x16 (&acc)[TM][TN], AF arow, BF brow, int K, char* smem, float& sumsq, bool pre, bool hasNext, AFN arowN, BFN browN) {
;     ...
;   const int t = tid_(), lane = t & 63, w = t >> 6, r = lane & 31, hh = lane >> 5;
;   const int wm = w % WM, wn = w / WM;
;   const int row0 = t >> 3;
;   const int c = (t & 7) ^ ((row0 >> 1) & 7);
;   const bool a0v = row0 < RA, a1v = row0 + 64 < RA, a2v = row0 + 128 < RA, a3v = row0 + 192 < RA;
;   const bool b0v = row0 < RB, b1v = row0 + 64 < RB, b2v = row0 + 128 < RB, b3v = row0 + 192 < RB;
;   const bf16_t* pa0 = arow(a0v ? row0 : 0) + c * 8;
;   const bf16_t* pa1 = arow(a1v ? row0 + 64 : 0) + c * 8;
;   const bf16_t* pa2 = arow(a2v ? row0 + 128 : 0) + c * 8;
;   const bf16_t* pa3 = arow(a3v ? row0 + 192 : 0) + c * 8;
;   const bf16_t* pb0 = brow(b0v ? row0 : 0) + c * 8;
;   const bf16_t* pb1 = brow(b1v ? row0 + 64 : 0) + c * 8;
;   const bf16_t* pb2 = brow(b2v ? row0 + 128 : 0) + c * 8;
;   const bf16_t* pb3 = brow(b3v ? row0 + 192 : 0) + c * 8;
;   if (!pre) {
;     char* l_ = smem + t * 16; char* m_ = l_ + RA * LDR;
;     if (a0v) GLDS(pa0, l_); if (a1v) GLDS(pa1, l_ + 8192); if (a2v) GLDS(pa2, l_ + 16384); if (a3v) GLDS(pa3, l_ + 24576);
;     if (b0v) GLDS(pb0, m_); if (b1v) GLDS(pb1, m_ + 8192); if (b2v) GLDS(pb2, m_ + 16384); if (b3v) GLDS(pb3, m_ + 24576);
;   }
;   if (NST == 3) {
;     char* l_ = smem + STAGE + t * 16; char* m_ = l_ + RA * LDR;
;     GLDS(pa0 + 64, l_); GLDS(pa1 + 64, l_ + 8192); GLDS(pa2 + 64, l_ + 16384); GLDS(pa3 + 64, l_ + 24576);
;     GLDS(pb0 + 64, m_); GLDS(pb1 + 64, m_ + 8192);
;     asm volatile("s_waitcnt vmcnt(6)" ::: "memory");
;   } else wait_vm0();
;   bar_();
;   const int nk = K >> 6;
;   const int sw = (r >> 1) & 7;
;   const int aoff = (wm * TM * 32 + r) * LDR, boff = RA * LDR + (wn * TN * 32 + r) * LDR;
; DI void phase2(const Params& p, char* smem) {
;     ...
;     f32x16 acc[4][2];
; #pragma unroll
;     for (int a = 0; a < 4; ++a)
; #pragma unroll
;       for (int b = 0; b < 2; ++b) acc[a][b] = zero16();
.LBB0_222:
	v_ashrrev_i32_e32 v2, 6, v1
	v_lshrrev_b32_e32 v4, 31, v1
	v_add_u32_e32 v4, v2, v4
	v_and_b32_e32 v5, 0x3fffe, v4
	v_bfe_u32 v3, v1, 5, 1
	v_sub_u32_e32 v2, v2, v5
	v_lshrrev_b32_e32 v5, 1, v1
	v_bfe_u32 v6, v1, 1, 3
	v_lshlrev_b32_e32 v1, 7, v1
	v_and_b32_e32 v218, 0xf80, v1
	v_lshlrev_b32_e32 v1, 12, v4
	v_and_b32_e32 v219, 0xffffe000, v1
	v_bitop3_b32 v1, v5, v3, 7 bitop3:0x6c
	v_lshlrev_b32_e32 v216, 4, v1
	v_bitop3_b32 v1, v3, v6, 2 bitop3:0x36
	v_lshlrev_b32_e32 v215, 4, v1
	v_bitop3_b32 v1, v3, v6, 4 bitop3:0x36
	v_lshlrev_b32_e32 v214, 4, v1
	v_bitop3_b32 v1, v3, v6, 6 bitop3:0x36
	v_and_b32_e32 v0, 7, v0
	v_lshl_or_b32 v217, v2, 14, v218
	v_lshlrev_b32_e32 v213, 4, v1
	v_lshl_add_u64 v[2:3], s[46:47], 0, v[188:189]
	v_lshlrev_b32_e32 v0, 4, v0
	v_mov_b32_e32 v1, v185
	v_lshl_add_u64 v[2:3], v[2:3], 0, v[0:1]
	v_lshl_add_u64 v[196:197], s[26:27], 0, v[2:3]
	v_lshl_add_u64 v[2:3], s[46:47], 0, v[190:191]
	v_lshl_add_u64 v[2:3], v[2:3], 0, v[0:1]
	v_lshl_add_u64 v[198:199], s[26:27], 0, v[2:3]
	v_lshl_add_u64 v[2:3], s[46:47], 0, v[192:193]
	v_lshl_add_u64 v[2:3], v[2:3], 0, v[0:1]
	v_lshl_add_u64 v[200:201], s[26:27], 0, v[2:3]
	v_lshl_add_u64 v[2:3], s[46:47], 0, v[194:195]
	v_lshl_add_u64 v[2:3], v[2:3], 0, v[0:1]
	v_lshl_add_u64 v[202:203], s[26:27], 0, v[2:3]
	v_lshl_add_u64 v[2:3], s[44:45], 0, v[188:189]
	v_lshl_add_u64 v[2:3], v[2:3], 0, v[0:1]
	v_lshl_add_u64 v[204:205], s[28:29], 0, v[2:3]
	v_lshl_add_u64 v[2:3], s[44:45], 0, v[190:191]
	v_lshl_add_u64 v[2:3], v[2:3], 0, v[0:1]
	v_lshl_add_u64 v[206:207], s[28:29], 0, v[2:3]
	v_lshl_add_u64 v[2:3], s[44:45], 0, v[192:193]
	v_lshl_add_u64 v[2:3], v[2:3], 0, v[0:1]
	v_lshl_add_u64 v[208:209], s[28:29], 0, v[2:3]
	v_lshl_add_u64 v[2:3], s[44:45], 0, v[194:195]
	s_waitcnt vmcnt(0)
	v_lshl_add_u64 v[0:1], v[2:3], 0, v[0:1]
	v_lshl_add_u64 v[210:211], s[28:29], 0, v[0:1]
	v_mov_b32_e32 v0, 0
	v_or_b32_e32 v222, v218, v219
	s_mov_b32 s13, 0
	s_mov_b64 s[44:45], 0
	v_mov_b32_e32 v1, v0
	v_mov_b32_e32 v2, v0
	v_mov_b32_e32 v3, v0
	v_mov_b32_e32 v4, v0
	v_mov_b32_e32 v5, v0
	v_mov_b32_e32 v6, v0
	v_mov_b32_e32 v7, v0
	v_mov_b32_e32 v8, v0
	v_mov_b32_e32 v9, v0
	v_mov_b32_e32 v10, v0
	v_mov_b32_e32 v11, v0
	v_mov_b32_e32 v12, v0
	v_mov_b32_e32 v13, v0
	v_mov_b32_e32 v14, v0
	v_mov_b32_e32 v15, v0
	v_mov_b32_e32 v64, v0
	v_mov_b32_e32 v65, v0
	v_mov_b32_e32 v66, v0
	v_mov_b32_e32 v67, v0
	v_mov_b32_e32 v68, v0
	v_mov_b32_e32 v69, v0
	v_mov_b32_e32 v70, v0
	v_mov_b32_e32 v71, v0
	v_mov_b32_e32 v72, v0
	v_mov_b32_e32 v73, v0
	v_mov_b32_e32 v74, v0
	v_mov_b32_e32 v75, v0
	v_mov_b32_e32 v76, v0
	v_mov_b32_e32 v77, v0
	v_mov_b32_e32 v78, v0
	v_mov_b32_e32 v79, v0
	v_mov_b32_e32 v16, v0
	v_mov_b32_e32 v17, v0
	v_mov_b32_e32 v18, v0
	v_mov_b32_e32 v19, v0
	v_mov_b32_e32 v20, v0
	v_mov_b32_e32 v21, v0
	v_mov_b32_e32 v22, v0
	v_mov_b32_e32 v23, v0
	v_mov_b32_e32 v24, v0
	v_mov_b32_e32 v25, v0
	v_mov_b32_e32 v26, v0
	v_mov_b32_e32 v27, v0
	v_mov_b32_e32 v28, v0
	v_mov_b32_e32 v29, v0
	v_mov_b32_e32 v30, v0
	v_mov_b32_e32 v31, v0
	v_mov_b32_e32 v80, v0
	v_mov_b32_e32 v81, v0
	v_mov_b32_e32 v82, v0
	v_mov_b32_e32 v83, v0
	v_mov_b32_e32 v84, v0
	v_mov_b32_e32 v85, v0
	v_mov_b32_e32 v86, v0
	v_mov_b32_e32 v87, v0
	v_mov_b32_e32 v88, v0
	v_mov_b32_e32 v89, v0
	v_mov_b32_e32 v90, v0
	v_mov_b32_e32 v91, v0
	v_mov_b32_e32 v92, v0
	v_mov_b32_e32 v93, v0
	v_mov_b32_e32 v94, v0
	v_mov_b32_e32 v95, v0
	v_mov_b32_e32 v32, v0
	v_mov_b32_e32 v33, v0
	v_mov_b32_e32 v34, v0
	v_mov_b32_e32 v35, v0
	v_mov_b32_e32 v36, v0
	v_mov_b32_e32 v37, v0
	v_mov_b32_e32 v38, v0
	v_mov_b32_e32 v39, v0
	v_mov_b32_e32 v40, v0
	v_mov_b32_e32 v41, v0
	v_mov_b32_e32 v42, v0
	v_mov_b32_e32 v43, v0
	v_mov_b32_e32 v44, v0
	v_mov_b32_e32 v45, v0
	v_mov_b32_e32 v46, v0
	v_mov_b32_e32 v47, v0
	v_mov_b32_e32 v96, v0
	v_mov_b32_e32 v97, v0
	v_mov_b32_e32 v98, v0
	v_mov_b32_e32 v99, v0
	v_mov_b32_e32 v100, v0
	v_mov_b32_e32 v101, v0
	v_mov_b32_e32 v102, v0
	v_mov_b32_e32 v103, v0
	v_mov_b32_e32 v104, v0
	v_mov_b32_e32 v105, v0
	v_mov_b32_e32 v106, v0
	v_mov_b32_e32 v107, v0
	v_mov_b32_e32 v108, v0
	v_mov_b32_e32 v109, v0
	v_mov_b32_e32 v110, v0
	v_mov_b32_e32 v111, v0
	v_mov_b32_e32 v48, v0
	v_mov_b32_e32 v49, v0
	v_mov_b32_e32 v50, v0
	v_mov_b32_e32 v51, v0
	v_mov_b32_e32 v52, v0
	v_mov_b32_e32 v53, v0
	v_mov_b32_e32 v54, v0
	v_mov_b32_e32 v55, v0
	v_mov_b32_e32 v56, v0
	v_mov_b32_e32 v57, v0
	v_mov_b32_e32 v58, v0
	v_mov_b32_e32 v59, v0
	v_mov_b32_e32 v60, v0
	v_mov_b32_e32 v61, v0
	v_mov_b32_e32 v62, v0
	v_mov_b32_e32 v63, v0
	v_mov_b32_e32 v112, v0
	v_mov_b32_e32 v113, v0
	v_mov_b32_e32 v114, v0
	v_mov_b32_e32 v115, v0
	v_mov_b32_e32 v116, v0
	v_mov_b32_e32 v117, v0
	v_mov_b32_e32 v118, v0
	v_mov_b32_e32 v119, v0
	v_mov_b32_e32 v120, v0
	v_mov_b32_e32 v121, v0
	v_mov_b32_e32 v122, v0
	v_mov_b32_e32 v123, v0
	v_mov_b32_e32 v124, v0
	v_mov_b32_e32 v125, v0
	v_mov_b32_e32 v126, v0
	v_mov_b32_e32 v127, v0
	s_barrier
	v_readfirstlane_b32 s66, v212
	s_and_b32 s37, s13, 0x10000
	v_add_u32_e32 v225, s37, v222
	v_add_u32_e32 v224, s37, v217
	s_xor_b32 s37, s37, 0x10000
	s_add_i32 s37, s37, s66
	v_add_u32_e32 v226, v225, v216
	v_add_u32_e32 v227, v224, v216
	ds_read_b128 v[164:167], v226 offset:32768
	ds_read_b128 v[172:175], v227
	ds_read_b128 v[156:159], v226 offset:36864
	ds_read_b128 v[168:171], v227 offset:4096
	ds_read_b128 v[160:163], v227 offset:8192
	ds_read_b128 v[152:155], v227 offset:12288
	s_mov_b32 m0, s37
	v_lshl_add_u64 v[228:229], v[196:197], 0, s[44:45]
	global_load_lds_dwordx4 v[228:229], off
	s_add_u32 m0, s37, 0x2000
	v_lshl_add_u64 v[230:231], v[198:199], 0, s[44:45]
	global_load_lds_dwordx4 v[230:231], off
	s_add_u32 m0, s37, 0x4000
	v_lshl_add_u64 v[228:229], v[200:201], 0, s[44:45]
	global_load_lds_dwordx4 v[228:229], off
	s_add_u32 m0, s37, 0x6000
	v_lshl_add_u64 v[230:231], v[202:203], 0, s[44:45]
	global_load_lds_dwordx4 v[230:231], off
	s_add_u32 m0, s37, 0x8000
	v_lshl_add_u64 v[228:229], v[204:205], 0, s[44:45]
	global_load_lds_dwordx4 v[228:229], off
	s_add_u32 m0, s37, 0xa000
	v_lshl_add_u64 v[230:231], v[206:207], 0, s[44:45]
	global_load_lds_dwordx4 v[230:231], off
	s_add_u32 m0, s37, 0xc000
	v_lshl_add_u64 v[228:229], v[208:209], 0, s[44:45]
	global_load_lds_dwordx4 v[228:229], off
	s_add_u32 m0, s37, 0xe000
	v_lshl_add_u64 v[230:231], v[210:211], 0, s[44:45]
	global_load_lds_dwordx4 v[230:231], off
	s_branch .Lp2_g0
; DI void wait_vm0() { asm volatile("s_waitcnt vmcnt(0)" ::: "memory"); }
; DI void bar_() { __builtin_amdgcn_s_barrier(); }
; #define GLDS(gp, lp) __builtin_amdgcn_global_load_lds((const unsigned*)(gp), (__attribute__((address_space(3))) unsigned*)(lp), 16, 0, 0)
; #define SB_ __builtin_amdgcn_sched_barrier(0)
; #define LOADF(A_, B_, ks) do { const int po_ = (((ks) * 2 + hh) ^ sw) * 16; \
;       _Pragma("unroll") for (int tm = 0; tm < TM; ++tm) A_[tm] = *(const bf16x8*)(As + tm * 32 * LDR + po_); \
;       _Pragma("unroll") for (int tn = 0; tn < TN; ++tn) B_[tn] = *(const bf16x8*)(Bs + tn * 32 * LDR + po_); } while (0)
; template <int TM, int TN, int WM, int WN, bool SUMSQ, int NST, class AF, class BF, class AFN, class BFN>
; DI void gemm8x(f32x16 (&acc)[TM][TN], AF arow, BF brow, int K, char* smem, float& sumsq, bool pre, bool hasNext, AFN arowN, BFN browN) {
;     ...
;   auto compute = [&](const char* cur, char* nxt, bool issue, const bf16_t* q0, const bf16_t* q1, const bf16_t* q2, const bf16_t* q3,
;                      const bf16_t* s0, const bf16_t* s1, const bf16_t* s2, const bf16_t* s3) {
;     const char* As = cur + aoff;
;     const char* Bs = cur + boff;
;     char* l_ = nxt + t * 16; char* m_ = l_ + RA * LDR;
;     bf16x8 a0[TM], b0[TN], a1[TM], b1[TN];
;     ...
;     LOADF(a0, b0, 0);
;     LOADF(a1, b1, 1);
;     SB_;
;     if (issue) { if (a0v) GLDS(q0, l_); if (a1v) GLDS(q1, l_ + 8192); }
;     SB_;
;     __builtin_amdgcn_s_setprio(1);
;     MMF(a0, b0);
;     LOADF(a0, b0, 2);
;     SB_;
;     if (issue) { if (a2v) GLDS(q2, l_ + 16384); if (a3v) GLDS(q3, l_ + 24576); }
;     SB_;
;     MMF(a1, b1);
;     LOADF(a1, b1, 3);
;     SB_;
;     if (issue) { if (b0v) GLDS(s0, m_); if (b1v) GLDS(s1, m_ + 8192); }
;     SB_;
;     MMF(a0, b0);
;     SB_;
;     if (issue) { if (b2v) GLDS(s2, m_ + 16384); if (b3v) GLDS(s3, m_ + 24576); }
;     SB_;
;     MMF(a1, b1);
;     __builtin_amdgcn_s_setprio(0);
;   };
;   int sc_ = 0;
;   for (int kt = 0; kt < nk - 1; ++kt) {
;     SB_;
;     if (NST == 2) {
;       const int ko = (kt + 1) * 64;
;       compute(smem + (kt & 1) * STAGE, smem + ((kt + 1) & 1) * STAGE, true, pa0 + ko, pa1 + ko, pa2 + ko, pa3 + ko, pb0 + ko, pb1 + ko, pb2 + ko, pb3 + ko);
;       SB_;
;       wait_vm0(); bar_();
.Lp2_loop:
	s_and_b32 s37, s13, 0x10000
	v_add_u32_e32 v225, s37, v222
	v_add_u32_e32 v224, s37, v217
	s_xor_b32 s37, s37, 0x10000
	s_add_i32 s37, s37, s66
	v_add_u32_e32 v226, v225, v216
	v_add_u32_e32 v227, v224, v216
	s_setprio 1
	v_mfma_f32_32x32x16_bf16 v[112:127], v[148:151], v[140:143], v[112:127]
	ds_read_b128 v[164:167], v226 offset:32768
	ds_read_b128 v[172:175], v227
	s_mov_b32 m0, s37
	v_lshl_add_u64 v[228:229], v[196:197], 0, s[44:45]
	global_load_lds_dwordx4 v[228:229], off
	v_mfma_f32_32x32x16_bf16 v[48:63], v[148:151], v[132:135], v[48:63]
	ds_read_b128 v[156:159], v226 offset:36864
	ds_read_b128 v[168:171], v227 offset:4096
	s_add_u32 m0, s37, 0x2000
	v_lshl_add_u64 v[230:231], v[198:199], 0, s[44:45]
	global_load_lds_dwordx4 v[230:231], off
	v_mfma_f32_32x32x16_bf16 v[96:111], v[144:147], v[140:143], v[96:111]
	ds_read_b128 v[160:163], v227 offset:8192
	s_add_u32 m0, s37, 0x4000
	v_lshl_add_u64 v[228:229], v[200:201], 0, s[44:45]
	global_load_lds_dwordx4 v[228:229], off
	v_mfma_f32_32x32x16_bf16 v[32:47], v[144:147], v[132:135], v[32:47]
	ds_read_b128 v[152:155], v227 offset:12288
	s_add_u32 m0, s37, 0x6000
	v_lshl_add_u64 v[230:231], v[202:203], 0, s[44:45]
	global_load_lds_dwordx4 v[230:231], off
	v_mfma_f32_32x32x16_bf16 v[80:95], v[136:139], v[140:143], v[80:95]
	s_add_u32 m0, s37, 0x8000
	v_lshl_add_u64 v[228:229], v[204:205], 0, s[44:45]
	global_load_lds_dwordx4 v[228:229], off
	v_mfma_f32_32x32x16_bf16 v[16:31], v[136:139], v[132:135], v[16:31]
	s_add_u32 m0, s37, 0xa000
	v_lshl_add_u64 v[230:231], v[206:207], 0, s[44:45]
	global_load_lds_dwordx4 v[230:231], off
	v_mfma_f32_32x32x16_bf16 v[64:79], v[128:131], v[140:143], v[64:79]
	s_add_u32 m0, s37, 0xc000
	v_lshl_add_u64 v[228:229], v[208:209], 0, s[44:45]
	global_load_lds_dwordx4 v[228:229], off
	v_mfma_f32_32x32x16_bf16 v[0:15], v[128:131], v[132:135], v[0:15]
	s_add_u32 m0, s37, 0xe000
	v_lshl_add_u64 v[230:231], v[210:211], 0, s[44:45]
	global_load_lds_dwordx4 v[230:231], off
.Lp2_g0:
	s_setprio 1
	v_add_u32_e32 v226, v225, v215
	v_add_u32_e32 v227, v224, v215
	s_waitcnt lgkmcnt(0)
	v_mfma_f32_32x32x16_bf16 v[112:127], v[172:175], v[164:167], v[112:127]
	ds_read_b128 v[140:143], v226 offset:32768
	ds_read_b128 v[148:151], v227
	v_mfma_f32_32x32x16_bf16 v[48:63], v[172:175], v[156:159], v[48:63]
	ds_read_b128 v[132:135], v226 offset:36864
	ds_read_b128 v[144:147], v227 offset:4096
	v_mfma_f32_32x32x16_bf16 v[96:111], v[168:171], v[164:167], v[96:111]
	ds_read_b128 v[136:139], v227 offset:8192
	v_mfma_f32_32x32x16_bf16 v[32:47], v[168:171], v[156:159], v[32:47]
	ds_read_b128 v[128:131], v227 offset:12288
	v_mfma_f32_32x32x16_bf16 v[80:95], v[160:163], v[164:167], v[80:95]
	v_mfma_f32_32x32x16_bf16 v[16:31], v[160:163], v[156:159], v[16:31]
	v_mfma_f32_32x32x16_bf16 v[64:79], v[152:155], v[164:167], v[64:79]
	v_mfma_f32_32x32x16_bf16 v[0:15], v[152:155], v[156:159], v[0:15]
	v_add_u32_e32 v226, v225, v214
	v_add_u32_e32 v227, v224, v214
	s_waitcnt lgkmcnt(0)
	v_mfma_f32_32x32x16_bf16 v[112:127], v[148:151], v[140:143], v[112:127]
	ds_read_b128 v[164:167], v226 offset:32768
	ds_read_b128 v[172:175], v227
	v_mfma_f32_32x32x16_bf16 v[48:63], v[148:151], v[132:135], v[48:63]
	ds_read_b128 v[156:159], v226 offset:36864
	ds_read_b128 v[168:171], v227 offset:4096
	v_mfma_f32_32x32x16_bf16 v[96:111], v[144:147], v[140:143], v[96:111]
	ds_read_b128 v[160:163], v227 offset:8192
	v_mfma_f32_32x32x16_bf16 v[32:47], v[144:147], v[132:135], v[32:47]
	ds_read_b128 v[152:155], v227 offset:12288
	v_mfma_f32_32x32x16_bf16 v[80:95], v[136:139], v[140:143], v[80:95]
	v_mfma_f32_32x32x16_bf16 v[16:31], v[136:139], v[132:135], v[16:31]
	v_mfma_f32_32x32x16_bf16 v[64:79], v[128:131], v[140:143], v[64:79]
	v_mfma_f32_32x32x16_bf16 v[0:15], v[128:131], v[132:135], v[0:15]
	v_add_u32_e32 v226, v225, v213
	v_add_u32_e32 v227, v224, v213
	s_waitcnt lgkmcnt(0)
	v_mfma_f32_32x32x16_bf16 v[112:127], v[172:175], v[164:167], v[112:127]
	ds_read_b128 v[140:143], v226 offset:32768
	ds_read_b128 v[148:151], v227
	v_mfma_f32_32x32x16_bf16 v[48:63], v[172:175], v[156:159], v[48:63]
	ds_read_b128 v[132:135], v226 offset:36864
	ds_read_b128 v[144:147], v227 offset:4096
	v_mfma_f32_32x32x16_bf16 v[96:111], v[168:171], v[164:167], v[96:111]
	ds_read_b128 v[136:139], v227 offset:8192
	v_mfma_f32_32x32x16_bf16 v[32:47], v[168:171], v[156:159], v[32:47]
	ds_read_b128 v[128:131], v227 offset:12288
	v_mfma_f32_32x32x16_bf16 v[80:95], v[160:163], v[164:167], v[80:95]
	v_mfma_f32_32x32x16_bf16 v[16:31], v[160:163], v[156:159], v[16:31]
	v_mfma_f32_32x32x16_bf16 v[64:79], v[152:155], v[164:167], v[64:79]
	v_mfma_f32_32x32x16_bf16 v[0:15], v[152:155], v[156:159], v[0:15]
	s_setprio 0
	s_waitcnt vmcnt(0) lgkmcnt(0)
	s_add_i32 s13, s13, 0x10000
	s_add_u32 s44, s44, 0x80
	s_addc_u32 s45, s45, 0
	s_cmpk_eq_i32 s44, 0x780
	s_barrier
	s_cbranch_scc0 .Lp2_loop
; DI void lds_sync() { wait_lgkm0(); bar_(); }
; #define GLDS(gp, lp) __builtin_amdgcn_global_load_lds((const unsigned*)(gp), (__attribute__((address_space(3))) unsigned*)(lp), 16, 0, 0)
; #define SB_ __builtin_amdgcn_sched_barrier(0)
; template <int TM, int TN, int WM, int WN, bool SUMSQ, int NST, class AF, class BF, class AFN, class BFN>
; DI void gemm8x(f32x16 (&acc)[TM][TN], AF arow, BF brow, int K, char* smem, float& sumsq, bool pre, bool hasNext, AFN arowN, BFN browN) {
;     ...
;   auto compute = [&](const char* cur, char* nxt, bool issue, const bf16_t* q0, const bf16_t* q1, const bf16_t* q2, const bf16_t* q3,
;                      const bf16_t* s0, const bf16_t* s1, const bf16_t* s2, const bf16_t* s3) {
;     const char* As = cur + aoff;
;     const char* Bs = cur + boff;
;     char* l_ = nxt + t * 16; char* m_ = l_ + RA * LDR;
;     bf16x8 a0[TM], b0[TN], a1[TM], b1[TN];
;     ...
;     LOADF(a0, b0, 0);
;     LOADF(a1, b1, 1);
;     SB_;
;     if (issue) { if (a0v) GLDS(q0, l_); if (a1v) GLDS(q1, l_ + 8192); }
;     SB_;
;     __builtin_amdgcn_s_setprio(1);
;     MMF(a0, b0);
;     LOADF(a0, b0, 2);
;     SB_;
;     if (issue) { if (a2v) GLDS(q2, l_ + 16384); if (a3v) GLDS(q3, l_ + 24576); }
;     SB_;
;     MMF(a1, b1);
;     LOADF(a1, b1, 3);
;     SB_;
;     if (issue) { if (b0v) GLDS(s0, m_); if (b1v) GLDS(s1, m_ + 8192); }
;     SB_;
;     MMF(a0, b0);
;     SB_;
;     if (issue) { if (b2v) GLDS(s2, m_ + 16384); if (b3v) GLDS(s3, m_ + 24576); }
;     SB_;
;     MMF(a1, b1);
;     ...
;     const bf16_t *q0 = pa0, *q1 = pa0, *q2 = pa0, *q3 = pa0, *s0 = pa0, *s1 = pa0, *s2 = pa0, *s3 = pa0;
;     if (hasNext) {
;       q0 = arowN(a0v ? row0 : 0) + c * 8; q1 = arowN(a1v ? row0 + 64 : 0) + c * 8; q2 = arowN(a2v ? row0 + 128 : 0) + c * 8; q3 = arowN(a3v ? row0 + 192 : 0) + c * 8;
;       s0 = browN(b0v ? row0 : 0) + c * 8; s1 = browN(b1v ? row0 + 64 : 0) + c * 8; s2 = browN(b2v ? row0 + 128 : 0) + c * 8; s3 = browN(b3v ? row0 + 192 : 0) + c * 8;
;     }
;     SB_;
;     compute(smem + ((nk - 1) & 1) * STAGE, smem, hasNext, q0, q1, q2, q3, s0, s1, s2, s3);
;     SB_;
;     lds_sync();
	s_and_b32 s37, s13, 0x10000
	v_add_u32_e32 v225, s37, v222
	v_add_u32_e32 v224, s37, v217
	s_xor_b32 s37, s37, 0x10000
	s_add_i32 s37, s37, s66
	v_add_u32_e32 v226, v225, v216
	v_add_u32_e32 v227, v224, v216
	s_setprio 1
	v_mfma_f32_32x32x16_bf16 v[112:127], v[148:151], v[140:143], v[112:127]
	ds_read_b128 v[164:167], v226 offset:32768
	ds_read_b128 v[172:175], v227
	v_mfma_f32_32x32x16_bf16 v[48:63], v[148:151], v[132:135], v[48:63]
	ds_read_b128 v[156:159], v226 offset:36864
	ds_read_b128 v[168:171], v227 offset:4096
	v_mfma_f32_32x32x16_bf16 v[96:111], v[144:147], v[140:143], v[96:111]
	ds_read_b128 v[160:163], v227 offset:8192
	v_mfma_f32_32x32x16_bf16 v[32:47], v[144:147], v[132:135], v[32:47]
	ds_read_b128 v[152:155], v227 offset:12288
	v_mfma_f32_32x32x16_bf16 v[80:95], v[136:139], v[140:143], v[80:95]
	v_mfma_f32_32x32x16_bf16 v[16:31], v[136:139], v[132:135], v[16:31]
	v_mfma_f32_32x32x16_bf16 v[64:79], v[128:131], v[140:143], v[64:79]
	v_mfma_f32_32x32x16_bf16 v[0:15], v[128:131], v[132:135], v[0:15]
	s_setprio 1
	v_add_u32_e32 v226, v225, v215
	v_add_u32_e32 v227, v224, v215
	s_waitcnt lgkmcnt(0)
	v_mfma_f32_32x32x16_bf16 v[112:127], v[172:175], v[164:167], v[112:127]
	ds_read_b128 v[140:143], v226 offset:32768
	ds_read_b128 v[148:151], v227
	v_mfma_f32_32x32x16_bf16 v[48:63], v[172:175], v[156:159], v[48:63]
	ds_read_b128 v[132:135], v226 offset:36864
	ds_read_b128 v[144:147], v227 offset:4096
	v_mfma_f32_32x32x16_bf16 v[96:111], v[168:171], v[164:167], v[96:111]
	ds_read_b128 v[136:139], v227 offset:8192
	v_mfma_f32_32x32x16_bf16 v[32:47], v[168:171], v[156:159], v[32:47]
	ds_read_b128 v[128:131], v227 offset:12288
	v_mfma_f32_32x32x16_bf16 v[80:95], v[160:163], v[164:167], v[80:95]
	v_mfma_f32_32x32x16_bf16 v[16:31], v[160:163], v[156:159], v[16:31]
	v_mfma_f32_32x32x16_bf16 v[64:79], v[152:155], v[164:167], v[64:79]
	v_mfma_f32_32x32x16_bf16 v[0:15], v[152:155], v[156:159], v[0:15]
	v_add_u32_e32 v226, v225, v214
	v_add_u32_e32 v227, v224, v214
	s_waitcnt lgkmcnt(0)
	v_mfma_f32_32x32x16_bf16 v[112:127], v[148:151], v[140:143], v[112:127]
	ds_read_b128 v[164:167], v226 offset:32768
	ds_read_b128 v[172:175], v227
	v_mfma_f32_32x32x16_bf16 v[48:63], v[148:151], v[132:135], v[48:63]
	ds_read_b128 v[156:159], v226 offset:36864
	ds_read_b128 v[168:171], v227 offset:4096
	v_mfma_f32_32x32x16_bf16 v[96:111], v[144:147], v[140:143], v[96:111]
	ds_read_b128 v[160:163], v227 offset:8192
	v_mfma_f32_32x32x16_bf16 v[32:47], v[144:147], v[132:135], v[32:47]
	ds_read_b128 v[152:155], v227 offset:12288
	v_mfma_f32_32x32x16_bf16 v[80:95], v[136:139], v[140:143], v[80:95]
	v_mfma_f32_32x32x16_bf16 v[16:31], v[136:139], v[132:135], v[16:31]
	v_mfma_f32_32x32x16_bf16 v[64:79], v[128:131], v[140:143], v[64:79]
	v_mfma_f32_32x32x16_bf16 v[0:15], v[128:131], v[132:135], v[0:15]
	v_add_u32_e32 v226, v225, v213
	v_add_u32_e32 v227, v224, v213
	s_waitcnt lgkmcnt(0)
	v_mfma_f32_32x32x16_bf16 v[112:127], v[172:175], v[164:167], v[112:127]
	ds_read_b128 v[140:143], v226 offset:32768
	ds_read_b128 v[148:151], v227
	v_mfma_f32_32x32x16_bf16 v[48:63], v[172:175], v[156:159], v[48:63]
	ds_read_b128 v[132:135], v226 offset:36864
	ds_read_b128 v[144:147], v227 offset:4096
	v_mfma_f32_32x32x16_bf16 v[96:111], v[168:171], v[164:167], v[96:111]
	ds_read_b128 v[136:139], v227 offset:8192
	v_mfma_f32_32x32x16_bf16 v[32:47], v[168:171], v[156:159], v[32:47]
	ds_read_b128 v[128:131], v227 offset:12288
	v_mfma_f32_32x32x16_bf16 v[80:95], v[160:163], v[164:167], v[80:95]
	v_mfma_f32_32x32x16_bf16 v[16:31], v[160:163], v[156:159], v[16:31]
	v_mfma_f32_32x32x16_bf16 v[64:79], v[152:155], v[164:167], v[64:79]
	v_mfma_f32_32x32x16_bf16 v[0:15], v[152:155], v[156:159], v[0:15]
	s_and_b64 vcc, exec, s[40:41]
	s_cbranch_vccz .Lp2_nonext
	s_mov_b32 s43, s31
	s_lshl_b64 s[42:43], s[42:43], 19
	s_add_u32 s42, s14, s42
	s_addc_u32 s43, s15, s43
	s_mov_b32 s13, s31
	v_lshl_add_u64 v[226:227], s[42:43], 0, v[188:189]
	s_lshl_b64 s[12:13], s[12:13], 19
	v_lshl_add_u64 v[186:187], v[226:227], 0, v[184:185]
	v_lshl_add_u64 v[226:227], s[42:43], 0, v[190:191]
	s_add_u32 s12, s16, s12
	v_lshl_add_u64 v[164:165], v[226:227], 0, v[184:185]
	v_lshl_add_u64 v[226:227], s[42:43], 0, v[192:193]
	s_addc_u32 s13, s17, s13
	v_lshl_add_u64 v[206:207], v[226:227], 0, v[184:185]
	v_lshl_add_u64 v[226:227], s[42:43], 0, v[194:195]
	v_lshl_add_u64 v[204:205], v[226:227], 0, v[184:185]
	v_lshl_add_u64 v[226:227], s[12:13], 0, v[188:189]
	v_lshl_add_u64 v[202:203], v[226:227], 0, v[184:185]
	v_lshl_add_u64 v[226:227], s[12:13], 0, v[190:191]
	v_lshl_add_u64 v[200:201], v[226:227], 0, v[184:185]
	v_lshl_add_u64 v[226:227], s[12:13], 0, v[192:193]
	v_lshl_add_u64 v[198:199], v[226:227], 0, v[184:185]
	v_lshl_add_u64 v[226:227], s[12:13], 0, v[194:195]
	v_lshl_add_u64 v[196:197], v[226:227], 0, v[184:185]
	s_mov_b32 m0, s66
	s_nop 0
	global_load_lds_dwordx4 v[186:187], off
	s_add_u32 m0, s66, 0x2000
	s_nop 0
	global_load_lds_dwordx4 v[164:165], off
	s_add_u32 m0, s66, 0x4000
	s_nop 0
	global_load_lds_dwordx4 v[206:207], off
	s_add_u32 m0, s66, 0x6000
	s_nop 0
	global_load_lds_dwordx4 v[204:205], off
	s_add_u32 m0, s66, 0x8000
	s_nop 0
	global_load_lds_dwordx4 v[202:203], off
	s_add_u32 m0, s66, 0xa000
	s_nop 0
	global_load_lds_dwordx4 v[200:201], off
	s_add_u32 m0, s66, 0xc000
	s_nop 0
	global_load_lds_dwordx4 v[198:199], off
	s_add_u32 m0, s66, 0xe000
	s_nop 0
	global_load_lds_dwordx4 v[196:197], off
.Lp2_nonext:
	s_waitcnt lgkmcnt(0)
	v_mfma_f32_32x32x16_bf16 v[112:127], v[148:151], v[140:143], v[112:127]
	v_mfma_f32_32x32x16_bf16 v[48:63], v[148:151], v[132:135], v[48:63]
	v_mfma_f32_32x32x16_bf16 v[96:111], v[144:147], v[140:143], v[96:111]
	v_mfma_f32_32x32x16_bf16 v[32:47], v[144:147], v[132:135], v[32:47]
	v_mfma_f32_32x32x16_bf16 v[80:95], v[136:139], v[140:143], v[80:95]
	v_mfma_f32_32x32x16_bf16 v[16:31], v[136:139], v[132:135], v[16:31]
	v_mfma_f32_32x32x16_bf16 v[64:79], v[128:131], v[140:143], v[64:79]
	v_mfma_f32_32x32x16_bf16 v[0:15], v[128:131], v[132:135], v[0:15]
	s_setprio 0
	s_waitcnt lgkmcnt(0)
	s_mov_b64 s[4:5], -1
	s_and_b64 vcc, exec, s[38:39]
	s_barrier
	s_cbranch_vccz .LBB0_268
	s_add_i32 s4, s30, 0xffffff00
	s_mul_hi_i32 s5, s4, 0x24000
	s_mul_i32 s4, s4, 0x24000
	s_add_u32 s4, s20, s4
	s_addc_u32 s5, s21, s5
	s_lshl_b32 s6, s36, 9
	s_add_u32 s4, s4, s6
	s_addc_u32 s5, s5, 0
	s_add_u32 s6, s4, 0xfffffd00
	s_addc_u32 s7, s5, -1
	s_cmp_eq_u32 s36, 1
	s_cselect_b32 s40, 32, 20
	s_cselect_b32 s41, 16, 0
	s_mov_b64 s[4:5], 0
